# band loops: V^T tiles waited for at a third barrier just before the first P.V, so their LDS-DMA latency hides behind the first QK and softmax
# speedup vs baseline: 1.0312x; 1.0056x over previous
.Lband_ldd2:
	v_cvt_f32_i32_e32 v51, s24
	v_mul_f32_e32 v51, 0xbf2aaaab, v51
	v_exp_f32_e32 v51, v51
	v_cvt_f32_i32_e32 v52, v54
	v_mul_f32_e32 v51, 0x3fb8aa3b, v51
	v_ldexp_f32 v51, v51, s9
	v_mul_f32_e64 v52, -v51, v52
	v_mul_f32_e32 v18, 0x00000000, v51
	v_mul_f32_e32 v19, 0x3f800000, v51
	v_mul_f32_e32 v20, 0x40000000, v51
	v_mul_f32_e32 v21, 0x40400000, v51
	v_mul_f32_e32 v22, 0x41000000, v51
	v_mul_f32_e32 v23, 0x41100000, v51
	v_mul_f32_e32 v24, 0x41200000, v51
	v_mul_f32_e32 v25, 0x41300000, v51
	v_mul_f32_e32 v26, 0x41800000, v51
	v_mul_f32_e32 v27, 0x41880000, v51
	v_mul_f32_e32 v28, 0x41900000, v51
	v_mul_f32_e32 v29, 0x41980000, v51
	v_mul_f32_e32 v30, 0x41c00000, v51
	v_mul_f32_e32 v31, 0x41c80000, v51
	v_mul_f32_e32 v32, 0x41d00000, v51
	v_mul_f32_e32 v33, 0x41d80000, v51
	v_readfirstlane_b32 s34, v18
	v_readfirstlane_b32 s35, v19
	v_readfirstlane_b32 s36, v20
	v_readfirstlane_b32 s37, v21
	v_readfirstlane_b32 s38, v22
	v_readfirstlane_b32 s39, v23
	v_readfirstlane_b32 s40, v24
	v_readfirstlane_b32 s41, v25
	v_readfirstlane_b32 s42, v26
	v_readfirstlane_b32 s43, v27
	v_readfirstlane_b32 s44, v28
	v_readfirstlane_b32 s45, v29
	v_readfirstlane_b32 s46, v30
	v_readfirstlane_b32 s47, v31
	v_readfirstlane_b32 s48, v32
	v_readfirstlane_b32 s49, v33
	v_add_u32_e32 v55, s15, v54
	v_lshlrev_b32_e32 v62, s14, v57
	v_lshl_add_u32 v62, v48, 3, v62
	v_lshlrev_b32_e32 v63, 4, v57
	v_mov_b32_e32 v49, 0xf149f2ca
	v_mov_b32_e32 v34, 0xf149f2ca
	v_mov_b32_e32 v50, 0
	v_mov_b32_e32 v146, 0
	v_mov_b32_e32 v147, 0
	v_mov_b32_e32 v148, 0
	v_mov_b32_e32 v149, 0
	v_mov_b32_e32 v150, 0
	v_mov_b32_e32 v151, 0
	v_mov_b32_e32 v152, 0
	v_mov_b32_e32 v153, 0
	v_mov_b32_e32 v154, 0
	v_mov_b32_e32 v155, 0
	v_mov_b32_e32 v156, 0
	v_mov_b32_e32 v157, 0
	v_mov_b32_e32 v158, 0
	v_mov_b32_e32 v159, 0
	v_mov_b32_e32 v160, 0
	v_mov_b32_e32 v161, 0
	v_mov_b32_e32 v184, 0
	v_mov_b32_e32 v185, 0
	v_mov_b32_e32 v186, 0
	v_mov_b32_e32 v187, 0
	v_mov_b32_e32 v188, 0
	v_mov_b32_e32 v189, 0
	v_mov_b32_e32 v190, 0
	v_mov_b32_e32 v191, 0
	v_mov_b32_e32 v192, 0
	v_mov_b32_e32 v193, 0
	v_mov_b32_e32 v194, 0
	v_mov_b32_e32 v195, 0
	v_mov_b32_e32 v196, 0
	v_mov_b32_e32 v197, 0
	v_mov_b32_e32 v198, 0
	v_mov_b32_e32 v199, 0
	s_cmp_lt_u32 s50, 4
	s_cbranch_scc1 .Lband_wk
	s_waitcnt vmcnt(12)
	s_branch .Lband_wd

.Lband_wd:
	s_barrier
	ds_read_b128 v[130:133], v70
	ds_read_b128 v[134:137], v71
	ds_read_b128 v[138:141], v72
	ds_read_b128 v[142:145], v73
	s_waitcnt lgkmcnt(0)
	s_cmp_lt_i32 s8, 4
	s_cbranch_scc1 .Lband_s0a
	ds_read_b128 v[2:5], v35 offset:0
	ds_read_b128 v[6:9], v36 offset:0
	ds_read_b128 v[10:13], v37 offset:0
	ds_read_b128 v[14:17], v38 offset:0
	s_waitcnt lgkmcnt(0)
	v_mfma_f32_32x32x16_bf16 v[18:33], v[2:5], v[130:133], 0
	v_mfma_f32_32x32x16_bf16 v[18:33], v[6:9], v[134:137], v[18:33]
	v_mfma_f32_32x32x16_bf16 v[18:33], v[10:13], v[138:141], v[18:33]
	v_mfma_f32_32x32x16_bf16 v[18:33], v[14:17], v[142:145], v[18:33]

.Lband_s0c:
	s_waitcnt vmcnt(0)
	s_barrier
	s_cmp_lt_i32 s8, 4
	s_cbranch_scc1 .Lband_s0b
	ds_read_b128 v[82:85], v74 offset:0
	ds_read_b128 v[86:89], v74 offset:1024
	ds_read_b128 v[90:93], v74 offset:2048
	ds_read_b128 v[94:97], v74 offset:3072
	s_waitcnt lgkmcnt(0)
	s_nop 1
	v_mfma_f32_32x32x16_bf16 v[146:161], v[82:85], v[18:21], v[146:161]
	v_mfma_f32_32x32x16_bf16 v[184:199], v[90:93], v[18:21], v[184:199]
	v_mfma_f32_32x32x16_bf16 v[146:161], v[86:89], v[22:25], v[146:161]
	v_mfma_f32_32x32x16_bf16 v[184:199], v[94:97], v[22:25], v[184:199]
